# pre-pass W' mm_tile jobs: all 16 K-chunk loads issued at job start with counted vmcnt waits (was 4 exposed round trips per job)
# speedup vs baseline: 1.0101x; 1.0101x over previous
; #define LAS __attribute__((address_space(3)))
; template <bool TRANS>
; __device__ __forceinline__ void mm_tile(LAS float* sm, int tid, const float* __restrict__ A, int lda, int r0, int rmax, int acol0, const float* __restrict__ Wm, int d0, void* dstv, int ldd, int n0, unsigned* cmaxw) {
;     ...
;     for (int i = 0; i < 2; ++i) { const int idx = tid + i * 512, rr = idx >> 4, c4 = idx & 15;
;         va[i] = (f32x4){0.f, 0.f, 0.f, 0.f}; if (r0 + rr < rmax) va[i] = *(const f32x4*)(A + (size_t)(r0 + rr) * lda + acol0 + c4 * 4);
;         vb[i] = *(const f32x4*)(Wm + (size_t)rr * 256 + d0 + c4 * 4); }
;     for (int cc = 0; cc < 256; cc += 64) {
; #pragma unroll
;         for (int i = 0; i < 2; ++i) { const int idx = tid + i * 512, rr = idx >> 4, c4 = idx & 15;
;             *(LAS f32x4*)(As + rr * 68 + c4 * 4) = va[i];
;             LAS float* q = Bt + (c4 * 4) * 68 + rr; q[0] = vb[i][0]; q[68] = vb[i][1]; q[136] = vb[i][2]; q[204] = vb[i][3]; }
;         __syncthreads();
;         if (cc + 64 < 256) {
; #pragma unroll
;             for (int i = 0; i < 2; ++i) { const int idx = tid + i * 512, rr = idx >> 4, c4 = idx & 15;
;                 va[i] = (f32x4){0.f, 0.f, 0.f, 0.f}; if (r0 + rr < rmax) va[i] = *(const f32x4*)(A + (size_t)(r0 + rr) * lda + acol0 + cc + 64 + c4 * 4);
;                 vb[i] = *(const f32x4*)(Wm + (size_t)(cc + 64 + rr) * 256 + d0 + c4 * 4); } }
.LBB0_23:
	s_or_b64 exec, exec, s[52:53]
	v_lshl_add_u64 v[10:11], v[54:55], 0, v[34:35]
	global_load_dwordx4 v[22:25], v[10:11], off
	v_mov_b64_e32 v[168:169], s[30:31]
	v_mad_i64_i32 v[168:169], s[52:53], v61, s61, v[168:169]
	v_lshl_add_u64 v[168:169], v[168:169], 0, v[26:27]
	v_mov_b64_e32 v[170:171], s[30:31]
	v_mad_i64_i32 v[170:171], s[52:53], v62, s61, v[170:171]
	v_lshl_add_u64 v[170:171], v[170:171], 0, v[26:27]
	v_mov_b64_e32 v[120:121], 0
	v_mov_b64_e32 v[122:123], 0
	v_mov_b64_e32 v[128:129], 0
	v_mov_b64_e32 v[130:131], 0
	s_and_saveexec_b64 s[98:99], s[2:3]
	global_load_dwordx4 v[120:123], v[168:169], off offset:256
	s_mov_b64 exec, s[98:99]
	v_lshl_add_u64 v[172:173], v[54:55], 0, v[38:39]
	global_load_dwordx4 v[124:127], v[172:173], off
	s_and_saveexec_b64 s[98:99], s[4:5]
	global_load_dwordx4 v[128:131], v[170:171], off offset:256
	s_mov_b64 exec, s[98:99]
	v_lshl_add_u64 v[172:173], v[54:55], 0, v[40:41]
	global_load_dwordx4 v[132:135], v[172:173], off
	v_mov_b64_e32 v[136:137], 0
	v_mov_b64_e32 v[138:139], 0
	v_mov_b64_e32 v[144:145], 0
	v_mov_b64_e32 v[146:147], 0
	s_and_saveexec_b64 s[98:99], s[2:3]
	global_load_dwordx4 v[136:139], v[168:169], off offset:512
	s_mov_b64 exec, s[98:99]
	v_lshl_add_u64 v[172:173], v[54:55], 0, v[44:45]
	global_load_dwordx4 v[140:143], v[172:173], off
	s_and_saveexec_b64 s[98:99], s[4:5]
	global_load_dwordx4 v[144:147], v[170:171], off offset:512
	s_mov_b64 exec, s[98:99]
	v_lshl_add_u64 v[172:173], v[54:55], 0, v[46:47]
	global_load_dwordx4 v[148:151], v[172:173], off
	v_mov_b64_e32 v[152:153], 0
	v_mov_b64_e32 v[154:155], 0
	v_mov_b64_e32 v[160:161], 0
	v_mov_b64_e32 v[162:163], 0
	s_and_saveexec_b64 s[98:99], s[2:3]
	global_load_dwordx4 v[152:155], v[168:169], off offset:768
	s_mov_b64 exec, s[98:99]
	v_lshl_add_u64 v[172:173], v[54:55], 0, v[48:49]
	global_load_dwordx4 v[156:159], v[172:173], off
	s_and_saveexec_b64 s[98:99], s[4:5]
	global_load_dwordx4 v[160:163], v[170:171], off offset:768
	s_mov_b64 exec, s[98:99]
	v_lshl_add_u64 v[172:173], v[54:55], 0, v[50:51]
	global_load_dwordx4 v[164:167], v[172:173], off
	v_add_u32_e32 v60, 0x4400, v1
	v_add_u32_e32 v59, 0x4400, v29
	v_mov_b32_e32 v10, 0
	v_mov_b32_e32 v14, 0
	v_mov_b32_e32 v15, 0
	v_mov_b32_e32 v16, 0
	v_mov_b32_e32 v17, 0
	s_waitcnt vmcnt(14)
	ds_write_b128 v56, v[2:5]
	s_waitcnt vmcnt(13)
	ds_write2_b32 v60, v6, v7 offset1:68
	ds_write2_b32 v60, v8, v9 offset0:136 offset1:204
	ds_write_b128 v57, v[18:21]
	s_waitcnt vmcnt(12)
	ds_write2_b32 v59, v22, v23 offset1:68
	ds_write2_b32 v59, v24, v25 offset0:136 offset1:204
	s_waitcnt lgkmcnt(0)
	s_barrier
	s_and_saveexec_b64 s[52:53], s[2:3]
	s_cbranch_execz .LBB0_25
	v_mov_b64_e32 v[2:3], s[30:31]
	v_mad_i64_i32 v[2:3], s[0:1], v61, s61, v[2:3]
	v_lshl_add_u64 v[2:3], v[2:3], 0, v[26:27]
.LBB0_25:
	s_or_b64 exec, exec, s[52:53]
	v_lshl_add_u64 v[2:3], v[54:55], 0, v[38:39]
	v_mov_b32_e32 v11, 0
	v_mov_b32_e32 v12, 0
	v_mov_b32_e32 v13, 0
	s_and_saveexec_b64 s[52:53], s[4:5]
	s_cbranch_execz .LBB0_27
	v_mov_b64_e32 v[2:3], s[30:31]
	v_mad_i64_i32 v[2:3], s[0:1], v62, s61, v[2:3]
	v_lshl_add_u64 v[2:3], v[2:3], 0, v[26:27]
.LBB0_27:
	s_or_b64 exec, exec, s[52:53]
	v_lshl_add_u64 v[2:3], v[54:55], 0, v[40:41]
	ds_read_b128 v[64:67], v36
	ds_read_b128 v[68:71], v36 offset:16
	ds_read_b128 v[72:75], v58 offset:17408
	ds_read_b128 v[76:79], v58 offset:17424
	ds_read_b128 v[80:83], v58 offset:21760
	ds_read_b128 v[84:87], v58 offset:21776
	ds_read_b128 v[88:91], v36 offset:128
	ds_read_b128 v[92:95], v36 offset:144
	ds_read_b128 v[96:99], v58 offset:17536
	ds_read_b128 v[100:103], v58 offset:17552
	ds_read_b128 v[104:107], v58 offset:21888
	ds_read_b128 v[108:111], v58 offset:21904
	s_waitcnt lgkmcnt(0)
	s_barrier
	s_waitcnt vmcnt(10)
	ds_write_b128 v56, v[120:123]
	s_waitcnt vmcnt(9)
	ds_write2_b32 v60, v124, v125 offset1:68
	ds_write2_b32 v60, v126, v127 offset0:136 offset1:204
	ds_write_b128 v57, v[128:131]
	v_cvt_pk_bf16_f32 v10, v64, v65
	v_cvt_pk_bf16_f32 v11, v66, v67
	v_cvt_pk_bf16_f32 v12, v68, v69
	v_cvt_pk_bf16_f32 v13, v70, v71
	v_cvt_pk_bf16_f32 v14, v72, v73
	v_cvt_pk_bf16_f32 v15, v74, v75
	v_cvt_pk_bf16_f32 v16, v76, v77
	v_cvt_pk_bf16_f32 v17, v78, v79
	v_cvt_pk_bf16_f32 v18, v80, v81
	v_cvt_pk_bf16_f32 v19, v82, v83
	v_cvt_pk_bf16_f32 v20, v84, v85
	v_cvt_pk_bf16_f32 v21, v86, v87
	v_cvt_pk_bf16_f32 v64, v88, v89
	v_cvt_pk_bf16_f32 v65, v90, v91
	v_cvt_pk_bf16_f32 v66, v92, v93
	v_cvt_pk_bf16_f32 v67, v94, v95
	v_mfma_f32_16x16x32_bf16 v[14:17], v[10:13], v[14:17], 0
	v_cvt_pk_bf16_f32 v68, v96, v97
	v_cvt_pk_bf16_f32 v69, v98, v99
	v_cvt_pk_bf16_f32 v70, v100, v101
	v_mfma_f32_16x16x32_bf16 v[18:21], v[10:13], v[18:21], 0
	v_cvt_pk_bf16_f32 v71, v102, v103
	v_cvt_pk_bf16_f32 v72, v104, v105
	v_cvt_pk_bf16_f32 v73, v106, v107
	v_cvt_pk_bf16_f32 v74, v108, v109
	v_cvt_pk_bf16_f32 v75, v110, v111
	v_mfma_f32_16x16x32_bf16 v[10:13], v[64:67], v[68:71], v[14:17]
	v_mov_b32_e32 v2, 0
	v_mov_b32_e32 v6, 0
	v_mov_b32_e32 v7, 0
	v_mfma_f32_16x16x32_bf16 v[14:17], v[64:67], v[72:75], v[18:21]
	v_mov_b32_e32 v8, 0
	v_mov_b32_e32 v9, 0
	s_waitcnt vmcnt(8)
	ds_write2_b32 v59, v132, v133 offset1:68
	ds_write2_b32 v59, v134, v135 offset0:136 offset1:204
	s_waitcnt lgkmcnt(0)
	s_barrier
	s_and_saveexec_b64 s[52:53], s[2:3]
	s_cbranch_execz .LBB0_29
	v_mov_b64_e32 v[4:5], s[30:31]
	v_mad_i64_i32 v[4:5], s[0:1], v61, s61, v[4:5]
	v_lshl_add_u64 v[4:5], v[4:5], 0, v[26:27]
.LBB0_29:
	s_or_b64 exec, exec, s[52:53]
	v_lshl_add_u64 v[4:5], v[54:55], 0, v[44:45]
	v_mov_b32_e32 v22, 0
	v_mov_b32_e32 v23, 0
	v_mov_b32_e32 v24, 0
	v_mov_b32_e32 v25, 0
	s_and_saveexec_b64 s[52:53], s[4:5]
	s_cbranch_execz .LBB0_31
	v_mov_b64_e32 v[4:5], s[30:31]
	v_mad_i64_i32 v[4:5], s[0:1], v62, s61, v[4:5]
	v_lshl_add_u64 v[4:5], v[4:5], 0, v[26:27]
; #define LAS __attribute__((address_space(3)))
; template <bool TRANS>
; __device__ __forceinline__ void mm_tile(LAS float* sm, int tid, const float* __restrict__ A, int lda, int r0, int rmax, int acol0, const float* __restrict__ Wm, int d0, void* dstv, int ldd, int n0, unsigned* cmaxw) {
;     ...
;     for (int cc = 0; cc < 256; cc += 64) {
; #pragma unroll
;         for (int i = 0; i < 2; ++i) { const int idx = tid + i * 512, rr = idx >> 4, c4 = idx & 15;
;             *(LAS f32x4*)(As + rr * 68 + c4 * 4) = va[i];
;             LAS float* q = Bt + (c4 * 4) * 68 + rr; q[0] = vb[i][0]; q[68] = vb[i][1]; q[136] = vb[i][2]; q[204] = vb[i][3]; }
;         __syncthreads();
;         if (cc + 64 < 256) {
; #pragma unroll
;             for (int i = 0; i < 2; ++i) { const int idx = tid + i * 512, rr = idx >> 4, c4 = idx & 15;
;                 va[i] = (f32x4){0.f, 0.f, 0.f, 0.f}; if (r0 + rr < rmax) va[i] = *(const f32x4*)(A + (size_t)(r0 + rr) * lda + acol0 + cc + 64 + c4 * 4);
;                 vb[i] = *(const f32x4*)(Wm + (size_t)(cc + 64 + rr) * 256 + d0 + c4 * 4); } }
; #pragma unroll
;         for (int ks = 0; ks < 2; ++ks) {
;             const LAS float* ap = As + (br * 16 + fr) * 68 + ks * 32 + fq * 8;
;             const f32x4 a0 = *(const LAS f32x4*)ap, a1 = *(const LAS f32x4*)(ap + 4);
;             u32x4 aw; aw.x = pk_bf16(a0[0], a0[1]); aw.y = pk_bf16(a0[2], a0[3]); aw.z = pk_bf16(a1[0], a1[1]); aw.w = pk_bf16(a1[2], a1[3]);
;             const bf16x8 af = __builtin_bit_cast(bf16x8, aw);
; #pragma unroll
;             for (int bb = 0; bb < 2; ++bb) {
;                 const LAS float* bp = Bt + ((bc0 + bb) * 16 + fr) * 68 + ks * 32 + fq * 8;
;                 const f32x4 b0 = *(const LAS f32x4*)bp, b1 = *(const LAS f32x4*)(bp + 4);
;                 u32x4 bw; bw.x = pk_bf16(b0[0], b0[1]); bw.y = pk_bf16(b0[2], b0[3]); bw.z = pk_bf16(b1[0], b1[1]); bw.w = pk_bf16(b1[2], b1[3]);
;                 const bf16x8 bf = __builtin_bit_cast(bf16x8, bw);
;                 if (bb == 0) acc0 = __builtin_amdgcn_mfma_f32_16x16x32_bf16(af, bf, acc0, 0, 0, 0);
;                 else acc1 = __builtin_amdgcn_mfma_f32_16x16x32_bf16(af, bf, acc1, 0, 0, 0);
;             }
;         }
;         __syncthreads();
;     }
.LBB0_31:
	s_or_b64 exec, exec, s[52:53]
	v_lshl_add_u64 v[4:5], v[54:55], 0, v[46:47]
	ds_read_b128 v[68:71], v36
	ds_read_b128 v[72:75], v36 offset:16
	ds_read_b128 v[76:79], v58 offset:17408
	ds_read_b128 v[80:83], v58 offset:17424
	ds_read_b128 v[84:87], v58 offset:21760
	ds_read_b128 v[88:91], v58 offset:21776
	ds_read_b128 v[92:95], v36 offset:128
	ds_read_b128 v[96:99], v36 offset:144
	ds_read_b128 v[100:103], v58 offset:17536
	ds_read_b128 v[104:107], v58 offset:17552
	ds_read_b128 v[108:111], v58 offset:21888
	ds_read_b128 v[112:115], v58 offset:21904
	s_waitcnt lgkmcnt(0)
	s_barrier
	s_waitcnt vmcnt(6)
	ds_write_b128 v56, v[136:139]
	s_waitcnt vmcnt(5)
	ds_write2_b32 v60, v140, v141 offset1:68
	ds_write2_b32 v60, v142, v143 offset0:136 offset1:204
	ds_write_b128 v57, v[144:147]
	v_cvt_pk_bf16_f32 v6, v68, v69
	v_cvt_pk_bf16_f32 v7, v70, v71
	v_cvt_pk_bf16_f32 v8, v72, v73
	v_cvt_pk_bf16_f32 v9, v74, v75
	v_cvt_pk_bf16_f32 v18, v76, v77
	v_cvt_pk_bf16_f32 v19, v78, v79
	v_cvt_pk_bf16_f32 v20, v80, v81
	v_cvt_pk_bf16_f32 v21, v82, v83
	v_cvt_pk_bf16_f32 v22, v84, v85
	v_cvt_pk_bf16_f32 v23, v86, v87
	v_cvt_pk_bf16_f32 v24, v88, v89
	v_cvt_pk_bf16_f32 v25, v90, v91
	v_cvt_pk_bf16_f32 v68, v92, v93
	v_cvt_pk_bf16_f32 v69, v94, v95
	v_cvt_pk_bf16_f32 v70, v96, v97
	v_cvt_pk_bf16_f32 v71, v98, v99
	v_mfma_f32_16x16x32_bf16 v[10:13], v[6:9], v[18:21], v[10:13]
	v_cvt_pk_bf16_f32 v18, v100, v101
	v_cvt_pk_bf16_f32 v19, v102, v103
	v_cvt_pk_bf16_f32 v20, v104, v105
	v_mfma_f32_16x16x32_bf16 v[14:17], v[6:9], v[22:25], v[14:17]
	v_cvt_pk_bf16_f32 v21, v106, v107
	v_cvt_pk_bf16_f32 v22, v108, v109
	v_cvt_pk_bf16_f32 v23, v110, v111
	v_cvt_pk_bf16_f32 v24, v112, v113
	v_cvt_pk_bf16_f32 v25, v114, v115
	v_mfma_f32_16x16x32_bf16 v[6:9], v[68:71], v[18:21], v[10:13]
	v_mov_b32_e32 v3, 0
	v_mov_b32_e32 v4, 0
	v_mov_b32_e32 v5, 0
	v_mfma_f32_16x16x32_bf16 v[10:13], v[68:71], v[22:25], v[14:17]
	s_waitcnt vmcnt(4)
	ds_write2_b32 v59, v148, v149 offset1:68
	ds_write2_b32 v59, v150, v151 offset0:136 offset1:204
	s_waitcnt lgkmcnt(0)
	s_barrier
	s_and_saveexec_b64 s[52:53], s[2:3]
	s_cbranch_execz .LBB0_33
	v_mov_b64_e32 v[2:3], s[30:31]
	v_mad_i64_i32 v[2:3], s[0:1], v61, s61, v[2:3]
	v_lshl_add_u64 v[2:3], v[2:3], 0, v[26:27]
.LBB0_33:
	s_or_b64 exec, exec, s[52:53]
	v_lshl_add_u64 v[14:15], v[54:55], 0, v[48:49]
	v_mov_b32_e32 v18, 0
	v_mov_b32_e32 v19, 0
	v_mov_b32_e32 v20, 0
	v_mov_b32_e32 v21, 0
	s_and_saveexec_b64 s[2:3], s[4:5]
	s_cbranch_execz .LBB0_35
	v_mov_b64_e32 v[18:19], s[30:31]
	v_mad_i64_i32 v[18:19], s[0:1], v62, s61, v[18:19]
	v_lshl_add_u64 v[18:19], v[18:19], 0, v[26:27]
; #define LAS __attribute__((address_space(3)))
; template <bool TRANS>
; __device__ __forceinline__ void mm_tile(LAS float* sm, int tid, const float* __restrict__ A, int lda, int r0, int rmax, int acol0, const float* __restrict__ Wm, int d0, void* dstv, int ldd, int n0, unsigned* cmaxw) {
;     ...
;     for (int cc = 0; cc < 256; cc += 64) {
; #pragma unroll
;         for (int i = 0; i < 2; ++i) { const int idx = tid + i * 512, rr = idx >> 4, c4 = idx & 15;
;             *(LAS f32x4*)(As + rr * 68 + c4 * 4) = va[i];
;             LAS float* q = Bt + (c4 * 4) * 68 + rr; q[0] = vb[i][0]; q[68] = vb[i][1]; q[136] = vb[i][2]; q[204] = vb[i][3]; }
;         __syncthreads();
;         if (cc + 64 < 256) {
; #pragma unroll
;             for (int i = 0; i < 2; ++i) { const int idx = tid + i * 512, rr = idx >> 4, c4 = idx & 15;
;                 va[i] = (f32x4){0.f, 0.f, 0.f, 0.f}; if (r0 + rr < rmax) va[i] = *(const f32x4*)(A + (size_t)(r0 + rr) * lda + acol0 + cc + 64 + c4 * 4);
;                 vb[i] = *(const f32x4*)(Wm + (size_t)(cc + 64 + rr) * 256 + d0 + c4 * 4); } }
; #pragma unroll
;         for (int ks = 0; ks < 2; ++ks) {
;             const LAS float* ap = As + (br * 16 + fr) * 68 + ks * 32 + fq * 8;
;             const f32x4 a0 = *(const LAS f32x4*)ap, a1 = *(const LAS f32x4*)(ap + 4);
;             u32x4 aw; aw.x = pk_bf16(a0[0], a0[1]); aw.y = pk_bf16(a0[2], a0[3]); aw.z = pk_bf16(a1[0], a1[1]); aw.w = pk_bf16(a1[2], a1[3]);
;             const bf16x8 af = __builtin_bit_cast(bf16x8, aw);
; #pragma unroll
;             for (int bb = 0; bb < 2; ++bb) {
;                 const LAS float* bp = Bt + ((bc0 + bb) * 16 + fr) * 68 + ks * 32 + fq * 8;
;                 const f32x4 b0 = *(const LAS f32x4*)bp, b1 = *(const LAS f32x4*)(bp + 4);
;                 u32x4 bw; bw.x = pk_bf16(b0[0], b0[1]); bw.y = pk_bf16(b0[2], b0[3]); bw.z = pk_bf16(b1[0], b1[1]); bw.w = pk_bf16(b1[2], b1[3]);
;                 const bf16x8 bf = __builtin_bit_cast(bf16x8, bw);
;                 if (bb == 0) acc0 = __builtin_amdgcn_mfma_f32_16x16x32_bf16(af, bf, acc0, 0, 0, 0);
;                 else acc1 = __builtin_amdgcn_mfma_f32_16x16x32_bf16(af, bf, acc1, 0, 0, 0);
;             }
;         }
;         __syncthreads();
;     }
; #pragma unroll
;     for (int bb = 0; bb < 2; ++bb) { const f32x4 cacc = bb ? acc1 : acc0; const int d = (bc0 + bb) * 16 + fr, rl = br * 16 + fq * 4;
.LBB0_35:
	s_or_b64 exec, exec, s[2:3]
	v_lshl_add_u64 v[22:23], v[54:55], 0, v[50:51]
	ds_read_b128 v[62:65], v36
	ds_read_b128 v[66:69], v36 offset:16
	ds_read_b128 v[70:73], v58 offset:17408
	ds_read_b128 v[74:77], v58 offset:17424
	ds_read_b128 v[78:81], v58 offset:21760
	ds_read_b128 v[82:85], v58 offset:21776
	ds_read_b128 v[86:89], v36 offset:128
	ds_read_b128 v[90:93], v36 offset:144
	ds_read_b128 v[94:97], v58 offset:17536
	ds_read_b128 v[98:101], v58 offset:17552
	ds_read_b128 v[102:105], v58 offset:21888
	ds_read_b128 v[106:109], v58 offset:21904
	s_waitcnt lgkmcnt(0)
	s_barrier
	s_waitcnt vmcnt(2)
	ds_write_b128 v56, v[152:155]
	s_waitcnt vmcnt(1)
	ds_write2_b32 v60, v156, v157 offset1:68
	ds_write2_b32 v60, v158, v159 offset0:136 offset1:204
	ds_write_b128 v57, v[160:163]
	v_cvt_pk_bf16_f32 v2, v62, v63
	v_cvt_pk_bf16_f32 v3, v64, v65
	v_cvt_pk_bf16_f32 v4, v66, v67
	v_cvt_pk_bf16_f32 v5, v68, v69
	v_cvt_pk_bf16_f32 v14, v70, v71
	v_cvt_pk_bf16_f32 v15, v72, v73
	v_cvt_pk_bf16_f32 v16, v74, v75
	v_cvt_pk_bf16_f32 v17, v76, v77
	v_cvt_pk_bf16_f32 v18, v78, v79
	v_cvt_pk_bf16_f32 v19, v80, v81
	v_cvt_pk_bf16_f32 v20, v82, v83
	v_cvt_pk_bf16_f32 v21, v84, v85
	v_cvt_pk_bf16_f32 v60, v86, v87
	v_cvt_pk_bf16_f32 v61, v88, v89
	v_cvt_pk_bf16_f32 v62, v90, v91
	v_cvt_pk_bf16_f32 v63, v92, v93
	v_mfma_f32_16x16x32_bf16 v[6:9], v[2:5], v[14:17], v[6:9]
	v_cvt_pk_bf16_f32 v14, v94, v95
	v_cvt_pk_bf16_f32 v15, v96, v97
	v_cvt_pk_bf16_f32 v16, v98, v99
	v_mfma_f32_16x16x32_bf16 v[2:5], v[2:5], v[18:21], v[10:13]
	v_cvt_pk_bf16_f32 v17, v100, v101
	s_lshl_b32 s0, s63, 8
	s_or_b32 s0, s0, s7
	v_cvt_pk_bf16_f32 v10, v102, v103
	v_cvt_pk_bf16_f32 v11, v104, v105
	v_cvt_pk_bf16_f32 v12, v106, v107
	v_cvt_pk_bf16_f32 v13, v108, v109
	v_mfma_f32_16x16x32_bf16 v[6:9], v[60:63], v[14:17], v[6:9]
	s_ashr_i32 s7, s6, 31
	s_lshl_b32 s1, s0, 2
	s_add_u32 s2, s54, s1
	v_mfma_f32_16x16x32_bf16 v[2:5], v[60:63], v[10:13], v[2:5]
	s_addc_u32 s3, s55, 0
	s_waitcnt vmcnt(0)
	ds_write2_b32 v59, v164, v165 offset1:68
	ds_write2_b32 v59, v166, v167 offset0:136 offset1:204
	s_waitcnt lgkmcnt(0)
	s_barrier
	ds_read_b128 v[10:13], v36
	ds_read_b128 v[14:17], v36 offset:16
	ds_read_b128 v[18:21], v58 offset:17408
	ds_read_b128 v[22:25], v58 offset:17424
	ds_read_b128 v[60:63], v58 offset:21760
	ds_read_b128 v[64:67], v58 offset:21776
	ds_read_b128 v[68:71], v36 offset:128
	ds_read_b128 v[72:75], v36 offset:144
	ds_read_b128 v[76:79], v58 offset:17536
	ds_read_b128 v[80:83], v58 offset:17552
	ds_read_b128 v[84:87], v58 offset:21888
	ds_read_b128 v[88:91], v58 offset:21904
	s_waitcnt lgkmcnt(11)
	v_cvt_pk_bf16_f32 v10, v10, v11
	v_cvt_pk_bf16_f32 v11, v12, v13
	s_waitcnt lgkmcnt(10)
	v_cvt_pk_bf16_f32 v12, v14, v15
	v_cvt_pk_bf16_f32 v13, v16, v17
	s_waitcnt lgkmcnt(9)
	v_cvt_pk_bf16_f32 v14, v18, v19
	v_cvt_pk_bf16_f32 v15, v20, v21
	s_waitcnt lgkmcnt(8)
	v_cvt_pk_bf16_f32 v16, v22, v23
	v_cvt_pk_bf16_f32 v17, v24, v25
	s_waitcnt lgkmcnt(5)
	v_cvt_pk_bf16_f32 v22, v68, v69
	v_cvt_pk_bf16_f32 v23, v70, v71
	s_waitcnt lgkmcnt(4)
	v_cvt_pk_bf16_f32 v24, v72, v73
	v_cvt_pk_bf16_f32 v25, v74, v75
	v_mfma_f32_16x16x32_bf16 v[6:9], v[10:13], v[14:17], v[6:9]
	s_waitcnt lgkmcnt(3)
	v_cvt_pk_bf16_f32 v14, v76, v77
	v_cvt_pk_bf16_f32 v15, v78, v79
	s_waitcnt lgkmcnt(2)
	v_cvt_pk_bf16_f32 v16, v80, v81
	v_cvt_pk_bf16_f32 v17, v82, v83
	v_cvt_pk_bf16_f32 v18, v60, v61
	v_cvt_pk_bf16_f32 v19, v62, v63
	v_mfma_f32_16x16x32_bf16 v[14:17], v[22:25], v[14:17], v[6:9]
	v_cvt_pk_bf16_f32 v20, v64, v65
	v_cvt_pk_bf16_f32 v21, v66, v67
	s_waitcnt lgkmcnt(0)
	v_lshl_add_u64 v[6:7], s[6:7], 1, v[52:53]
	v_mfma_f32_16x16x32_bf16 v[2:5], v[10:13], v[18:21], v[2:5]
	s_nop 2
	v_max_f32_e64 v8, |v17|, |v17|
	v_max_f32_e64 v9, |v16|, |v16|
	v_max_f32_e32 v8, v9, v8
	v_max3_f32 v8, |v14|, |v15|, v8
	ds_bpermute_b32 v9, v37, v8
	v_cvt_pk_bf16_f32 v10, v84, v85
	v_cvt_pk_bf16_f32 v11, v86, v87
	v_cvt_pk_bf16_f32 v12, v88, v89
	v_cvt_pk_bf16_f32 v13, v90, v91
	s_waitcnt lgkmcnt(0)
	v_max_f32_e32 v9, v9, v9
	v_max_f32_e32 v9, v8, v9
	v_mfma_f32_16x16x32_bf16 v[2:5], v[22:25], v[10:13], v[2:5]
	v_or_b32_e32 v10, s0, v42
	v_mul_u32_u24_e32 v10, 0x840, v10
	v_cvt_pk_bf16_f32 v12, v14, v15
	v_lshlrev_b32_e32 v14, 1, v10
	ds_bpermute_b32 v10, v43, v9
	v_mov_b32_e32 v15, v27
	v_cvt_pk_bf16_f32 v13, v16, v17
	v_lshl_add_u64 v[14:15], v[6:7], 0, v[14:15]
	v_lshlrev_b32_e32 v8, 2, v42
	s_barrier
	s_waitcnt lgkmcnt(0)
	global_store_dwordx2 v[14:15], v[12:13], off
	s_and_saveexec_b64 s[4:5], vcc
	s_cbranch_execz .LBB0_37
	v_max_f32_e32 v10, v10, v10
	v_max_f32_e32 v9, v9, v9
	v_max_f32_e32 v9, v9, v10
	global_atomic_umax v8, v9, s[2:3]
